# attention: bias-table gather addresses simplified (one v_cndmask between a per-tile byte base and precomputed default-minus-4J, ds_read_b32 offset:4J) - 14 fewer VALU per 8 gathers
# speedup vs baseline: 1.0199x; 1.0031x over previous
; #define LAS __attribute__((address_space(3)))
; __device__ __forceinline__ void attn_phase(const bf16_t* Q, const bf16_t* Kb, const bf16_t* VTa, const float* rpb, bf16_t* Y, LAS unsigned char* lds, int bx, int G, int tid, int wave, int lane) {
;     const int g = wave & 3, hf = wave >> 2;
;     const int fr = lane & 15, fq = lane >> 4;
;     const int cs = (g == 0) ? 0 : ((g == 1) ? 8 : ((g == 2) ? 24 : 32));
;     const int c = 16 * g + fr;
;     const int colstart = min(max(c - 8, 0), 48);
;     const int kc0 = cs + 8 * fq;
;     const int dci0 = kc0 - c + 15;
;     const int wlo = max(colstart - kc0, 0), wwd = max(min(colstart + 16 - kc0, 8) - wlo, 0);
;     LAS unsigned char* KL = lds; LAS unsigned char* VL = lds + 65536; LAS float* rl = (LAS float*)(lds + 131072);
;     const int lr = lane >> 3, lc = lane & 7;
;     ...
;                 float bia[8];
; #pragma unroll
;                 for (int j = 0; j < 8; ++j) bia[j] = rl[((unsigned)(j - wlo) < (unsigned)wwd) ? dr * 31 + dci0 + j : 480];
.LBB0_445:
	v_readlane_b32 s12, v254, 57
	v_readlane_b32 s13, v254, 58
	s_add_u32 s18, s0, 0x1fc00000
	v_lshrrev_b32_e32 v39, 4, v220
	v_cndmask_b32_e64 v0, 0, 1, s[12:13]
	v_cmp_ne_u32_e64 s[16:17], 1, v0
	s_addc_u32 s19, s1, 0
	v_and_b32_e32 v219, 15, v218
	v_writelane_b32 v163, s16, 43
	s_andn2_b64 vcc, exec, s[12:13]
	v_and_b32_e32 v43, 7, v218
	v_lshlrev_b32_e32 v40, 4, v39
	v_lshlrev_b32_e32 v38, 2, v39
	v_writelane_b32 v163, s17, 44
	s_cbranch_vccnz .LBB0_470
	v_lshl_or_b32 v47, s20, 4, v219
	v_sub_u32_e64 v0, v47, 8 clamp
	v_min_u32_e32 v2, 48, v0
	v_lshlrev_b32_e32 v0, 3, v39
	v_add_u32_e32 v3, s22, v0
	v_sub_u32_e32 v2, v2, v3
	v_add_u32_e32 v4, 16, v2
	v_min_i32_e32 v4, 8, v4
	v_max_i32_e32 v5, 0, v2
	s_add_u32 s62, s0, 0x17c00000
	v_sub_u32_e32 v2, v4, v5
	s_addc_u32 s63, s1, 0
	v_max_i32_e32 v7, 0, v2
	v_sub_u32_e32 v2, v3, v47
	v_writelane_b32 v163, s46, 47
	s_add_u32 s21, s0, 0x18c00000
	v_add_u32_e32 v46, 0xe8, v2
	v_lshlrev_b32_e32 v2, 1, v220
	v_writelane_b32 v163, s47, 48
	s_addc_u32 s83, s1, 0
	v_and_b32_e32 v3, 24, v2
	s_add_u32 s34, s0, 0x1ac00000
	v_readlane_b32 s12, v163, 39
	v_add_u32_e32 v3, s22, v3
	s_addc_u32 s35, s1, 0
	s_mulk_i32 s12, 0x7440
	v_and_or_b32 v11, v218, 3, v3
	v_bfe_u32 v3, v3, 3, 2
	v_and_b32_e32 v2, 4, v2
	s_add_u32 s16, s78, s12
	s_movk_i32 s12, 0x1d1
	v_mov_b32_e32 v41, v1
	v_bitop3_b32 v6, v3, v39, v2 bitop3:0x36
	s_addc_u32 s17, s79, 0
	v_lshrrev_b32_e32 v4, 2, v220
	v_cmp_gt_i32_e64 s[38:39], s12, v218
	v_lshl_add_u64 v[44:45], s[62:63], 0, v[40:41]
	v_lshlrev_b32_e32 v41, 4, v6
	v_or_b32_e32 v6, 4, v39
	s_lshr_b32 s12, s22, 3
	v_lshrrev_b32_e32 v42, 3, v220
	v_and_b32_e32 v9, 4, v4
	v_bitop3_b32 v2, v3, v6, v2 bitop3:0x36
	v_add_u32_e32 v6, s12, v39
	v_lshrrev_b32_e32 v8, 1, v218
	v_lshlrev_b32_e32 v55, 4, v2
	v_bitop3_b32 v2, v9, v43, s20 bitop3:0x36
	v_bitop3_b32 v6, v6, v8, 7 bitop3:0x78
	v_bitop3_b32 v8, v9, v43, 1 bitop3:0x36
	v_bitop3_b32 v12, v9, v43, 2 bitop3:0x36
	v_or_b32_e32 v56, 24, v42
	v_bitop3_b32 v9, v9, v43, 3 bitop3:0x36
	v_lshlrev_b32_e32 v14, 3, v9
	v_lshrrev_b32_e32 v9, 1, v56
	v_xor_b32_e32 v9, v9, v220
	v_lshlrev_b32_e32 v9, 3, v9
	v_or_b32_e32 v60, 40, v42
	v_and_b32_e32 v16, 56, v9
	v_lshrrev_b32_e32 v9, 1, v60
	v_xor_b32_e32 v9, v9, v220
	v_lshlrev_b32_e32 v9, 3, v9
	v_or_b32_e32 v64, 56, v42
	v_and_b32_e32 v18, 56, v9
	v_lshrrev_b32_e32 v9, 1, v64
	v_xor_b32_e32 v9, v9, v220
	v_lshlrev_b32_e32 v9, 3, v9
	v_lshl_or_b32 v48, s82, 3, v42
	v_and_b32_e32 v20, 56, v9
	v_sub_u32_e32 v9, 0, v5
	v_ashrrev_i32_e32 v49, 31, v48
	v_lshlrev_b32_e32 v3, 7, v219
	s_add_i32 s88, 0, 0x10000
	v_lshlrev_b32_e32 v6, 4, v6
	v_cmp_gt_u32_e64 s[40:41], v7, v9
	v_sub_u32_e32 v9, 1, v5
	v_lshlrev_b64 v[50:51], 11, v[48:49]
	v_add3_u32 v49, s88, v3, v6
	v_lshl_or_b32 v3, s20, 6, v220
	v_or_b32_e32 v52, 8, v42
	v_cmp_lt_u32_e64 s[42:43], v9, v7
	v_sub_u32_e32 v9, 2, v5
	s_lshl_b32 s30, s82, 10
	v_lshlrev_b32_e32 v57, 3, v3
	v_lshlrev_b32_e32 v59, 5, v3
	v_lshrrev_b32_e32 v3, 1, v48
	v_lshrrev_b32_e32 v10, 1, v52
	v_cmp_lt_u32_e64 s[44:45], v9, v7
	v_sub_u32_e32 v9, 3, v5
	s_add_i32 s84, 0, 0x20000
	v_lshl_add_u32 v194, v245, 2, s84
	v_add_u32_e32 v195, -4, v194
	v_add_u32_e32 v196, -8, v194
	v_add_u32_e32 v197, -12, v194
	v_add_u32_e32 v198, -16, v194
	v_add_u32_e32 v199, -20, v194
	v_add_u32_e32 v200, -24, v194
	v_add_u32_e32 v201, -28, v194
	s_and_b32 s85, s82, -4
	s_add_i32 s86, s30, 0
	s_and_b32 s87, s82, 4
	v_xor_b32_e32 v3, v3, v218
	v_xor_b32_e32 v6, v39, v220
	v_xor_b32_e32 v10, v10, v220
	v_cmp_lt_u32_e64 s[46:47], v9, v7
	v_sub_u32_e32 v9, 4, v5
	s_cmp_eq_u32 s85, 4
	v_bitop3_b32 v4, v4, v43, 4 bitop3:0x6c
	v_lshlrev_b32_e32 v6, 3, v6
	v_lshlrev_b32_e32 v10, 3, v10
	v_cmp_lt_u32_e64 s[48:49], v9, v7
	v_sub_u32_e32 v9, 5, v5
	v_lshlrev_b32_e32 v3, 4, v3
	v_readlane_b32 s13, v163, 40
	v_lshlrev_b32_e32 v2, 3, v2
	s_cselect_b64 s[36:37], -1, 0
	s_cmp_lt_u32 s82, 4
	v_lshlrev_b32_e32 v4, 3, v4
	v_and_b32_e32 v6, 56, v6
	v_lshlrev_b32_e32 v8, 3, v8
	v_and_b32_e32 v10, 56, v10
	v_lshlrev_b32_e32 v12, 3, v12
	v_cmp_lt_u32_e64 s[50:51], v9, v7
	v_sub_u32_e32 v9, 6, v5
	v_sub_u32_e32 v5, 7, v5
	v_and_b32_e32 v22, 0x70, v3
	v_mov_b32_e32 v23, v1
	v_lshl_add_u32 v53, v218, 2, s84
	s_cselect_b64 s[12:13], -1, 0
	s_add_i32 s88, s88, s30
	v_or_b32_e32 v54, 16, v42
	v_or_b32_e32 v58, 32, v42
	v_or_b32_e32 v62, 48, v42
	v_cmp_lt_u32_e64 s[52:53], v9, v7
	v_cmp_lt_u32_e64 s[54:55], v5, v7
	s_or_b32 s89, s85, 1
	s_or_b32 s90, s85, 2
	s_or_b32 s91, s82, 3
	v_lshl_add_u32 v61, v11, 7, 0
	v_lshl_add_u64 v[66:67], s[18:19], 0, v[0:1]
	v_lshl_add_u64 v[68:69], s[34:35], 0, v[22:23]
	v_lshlrev_b32_e32 v70, 1, v4
	v_lshlrev_b32_e32 v72, 1, v6
	v_lshlrev_b32_e32 v74, 1, v8
	v_lshlrev_b32_e32 v76, 1, v10
	v_lshlrev_b32_e32 v78, 1, v12
	v_lshlrev_b32_e32 v80, 1, v14
	v_lshlrev_b32_e32 v82, 1, v16
	v_lshlrev_b32_e32 v84, 1, v18
	v_lshlrev_b32_e32 v86, 1, v20
	v_lshlrev_b32_e32 v88, 1, v0
	v_lshlrev_b32_e32 v0, 1, v2
	v_lshlrev_b32_e32 v90, 1, v38
	s_mov_b32 s92, s2
	s_branch .LBB0_448

; #define LAS __attribute__((address_space(3)))
; #define MFMA16(a, b, c) __builtin_amdgcn_mfma_f32_16x16x32_bf16((a), (b), (c), 0, 0, 0)
; __device__ __forceinline__ int att_fk(int key) { return ((key >> 3) & 3) + 4 * ((key >> 1) & 1); }
; __device__ __forceinline__ void attn_phase(const bf16_t* Q, const bf16_t* Kb, const bf16_t* VTa, const float* rpb, bf16_t* Y, LAS unsigned char* lds, int bx, int G, int tid, int wave, int lane) {
;     ...
; #pragma unroll
;             for (int ii = 0; ii < 4; ++ii) {
;                 const int i = 4 * hf + ii, dr = rs + i - r + 7;
;                 float bia[8];
; #pragma unroll
;                 for (int j = 0; j < 8; ++j) bia[j] = rl[((unsigned)(j - wlo) < (unsigned)wwd) ? dr * 31 + dci0 + j : 480];
; #pragma unroll
;                 for (int ta = 0; ta < 2; ++ta) {
;                     const int key = cs + 8 * (fr >> 2) + 4 * ta + (fr & 3), fk = att_fk(key);
;                     const LAS unsigned char* kp = KL + ((rs + i) & 7) * 8192 + key * 128;
;                     const bf16x8 kf0 = *(const LAS bf16x8*)(kp + ((fq ^ fk) << 4)), kf1 = *(const LAS bf16x8*)(kp + (((4 + fq) ^ fk) << 4));
;                     f32x4 a = {0.f, 0.f, 0.f, 0.f};
;                     a = MFMA16(kf0, qf0, a); a = MFMA16(kf1, qf1, a);
; #pragma unroll
;                     for (int idx = 0; idx < 4; ++idx) { a[idx] += bia[4 * ta + idx]; mx = fmaxf(mx, a[idx]); }
;                     s[ii][ta] = a;
;                 }
;             }
.LBB0_451:
	s_max_i32 s31, s94, 4
	s_add_i32 s31, s31, -4
	s_max_i32 s56, s94, 3
	s_min_u32 s64, s31, 0x78
	s_add_i32 s56, s56, -3
	s_add_i32 s58, s95, s64
	s_add_i32 s59, s20, s64
	s_min_u32 s80, s56, 0x78
	s_cmp_lg_u32 s80, s64
	s_cselect_b64 s[56:57], -1, 0
	s_add_i32 s59, s30, s59
	s_add_i32 s60, s64, s85
	s_mul_i32 s61, s59, 31
	s_add_i32 s74, s61, 0xffffff27
	s_lshl_b32 s59, s60, 13
	s_and_b32 s75, s59, 0xe000
	v_add_u32_e32 v10, s74, v46
	s_waitcnt vmcnt(1)
	v_lshl_add_u32 v190, v10, 2, s84
	v_cndmask_b32_e64 v11, v194, v190, s[40:41]
	v_add_u32_e32 v14, s75, v61
	s_waitcnt lgkmcnt(0)
	s_barrier
	v_add_u32_e32 v19, v14, v55
	ds_read_b32 v63, v11
	v_add_u32_e32 v18, v14, v41
	ds_read_b128 v[14:17], v19
	v_cndmask_b32_e64 v11, v195, v190, s[42:43]
	ds_read_b32 v65, v11 offset:4
	v_cndmask_b32_e64 v11, v196, v190, s[44:45]
	ds_read_b32 v71, v11 offset:8
	v_cndmask_b32_e64 v11, v197, v190, s[46:47]
	ds_read_b32 v73, v11 offset:12
	v_cndmask_b32_e64 v11, v198, v190, s[48:49]
	ds_read_b32 v75, v11 offset:16
	v_cndmask_b32_e64 v11, v199, v190, s[50:51]
	ds_read_b32 v77, v11 offset:20
	v_cndmask_b32_e64 v11, v200, v190, s[52:53]
	v_cndmask_b32_e64 v10, v201, v190, s[54:55]
	ds_read_b32 v79, v11 offset:24
	ds_read_b32 v81, v10 offset:28
	ds_read_b128 v[10:13], v18
	s_waitcnt vmcnt(0) lgkmcnt(0)
	v_mfma_f32_16x16x32_bf16 v[10:13], v[10:13], v[6:9], 0
	s_add_i32 s59, s64, s89
	s_add_i32 vcc_hi, s61, 0xffffff46
	s_lshl_b32 s59, s59, 13
	v_mfma_f32_16x16x32_bf16 v[10:13], v[14:17], v[2:5], v[10:13]
	ds_read_b128 v[14:17], v18 offset:512
	ds_read_b128 v[18:21], v19 offset:512
	s_and_b32 vcc_lo, s59, 0xe000
	v_add_u32_e32 v22, vcc_lo, v61
	s_waitcnt lgkmcnt(1)
	v_mfma_f32_16x16x32_bf16 v[14:17], v[14:17], v[6:9], 0
	v_add_u32_e32 v27, v22, v55
	v_add_u32_e32 v26, v22, v41
	ds_read_b128 v[22:25], v27
	s_waitcnt lgkmcnt(1)
	v_mfma_f32_16x16x32_bf16 v[14:17], v[18:21], v[2:5], v[14:17]
	v_add_u32_e32 v18, vcc_hi, v46
	v_lshl_add_u32 v191, v18, 2, s84
	v_cndmask_b32_e64 v19, v194, v191, s[40:41]
	ds_read_b32 v83, v19
	v_cndmask_b32_e64 v19, v195, v191, s[42:43]
	ds_read_b32 v85, v19 offset:4
	v_cndmask_b32_e64 v19, v196, v191, s[44:45]
	ds_read_b32 v87, v19 offset:8
	v_cndmask_b32_e64 v19, v197, v191, s[46:47]
	ds_read_b32 v89, v19 offset:12
	v_cndmask_b32_e64 v19, v198, v191, s[48:49]
	ds_read_b32 v91, v19 offset:16
	v_cndmask_b32_e64 v19, v199, v191, s[50:51]
	ds_read_b32 v99, v19 offset:20
	v_cndmask_b32_e64 v19, v200, v191, s[52:53]
	v_cndmask_b32_e64 v18, v201, v191, s[54:55]
	ds_read_b32 v100, v19 offset:24
	ds_read_b32 v101, v18 offset:28
	ds_read_b128 v[18:21], v26
	s_waitcnt lgkmcnt(0)
	v_mfma_f32_16x16x32_bf16 v[18:21], v[18:21], v[6:9], 0
	s_add_i32 s59, s64, s90
	s_addk_i32 s61, 0xff65
	s_lshl_b32 s59, s59, 13
	v_mfma_f32_16x16x32_bf16 v[18:21], v[22:25], v[2:5], v[18:21]
	ds_read_b128 v[22:25], v26 offset:512
	ds_read_b128 v[26:29], v27 offset:512
	s_and_b32 s60, s59, 0xe000
	v_add_u32_e32 v30, s60, v61
	s_waitcnt lgkmcnt(1)
	v_mfma_f32_16x16x32_bf16 v[22:25], v[22:25], v[6:9], 0
	v_add_u32_e32 v35, v30, v55
	v_add_u32_e32 v34, v30, v41
	ds_read_b128 v[30:33], v35
	s_waitcnt lgkmcnt(1)
	v_mfma_f32_16x16x32_bf16 v[22:25], v[26:29], v[2:5], v[22:25]
	v_add_u32_e32 v26, s61, v46
	v_lshl_add_u32 v192, v26, 2, s84
	v_cndmask_b32_e64 v27, v194, v192, s[40:41]
	ds_read_b32 v102, v27
	v_cndmask_b32_e64 v27, v195, v192, s[42:43]
	ds_read_b32 v103, v27 offset:4
	v_cndmask_b32_e64 v27, v196, v192, s[44:45]
	ds_read_b32 v104, v27 offset:8
	v_cndmask_b32_e64 v27, v197, v192, s[46:47]
	ds_read_b32 v105, v27 offset:12
	v_cndmask_b32_e64 v27, v198, v192, s[48:49]
	ds_read_b32 v106, v27 offset:16
	v_cndmask_b32_e64 v27, v199, v192, s[50:51]
	ds_read_b32 v107, v27 offset:20
	v_cndmask_b32_e64 v27, v200, v192, s[52:53]
	v_cndmask_b32_e64 v26, v201, v192, s[54:55]
	ds_read_b32 v108, v27 offset:24
	ds_read_b32 v109, v26 offset:28
	ds_read_b128 v[26:29], v34
	s_waitcnt lgkmcnt(0)
	v_mfma_f32_16x16x32_bf16 v[26:29], v[26:29], v[6:9], 0
	s_add_i32 s58, s30, s58
	s_add_i32 s31, s64, s91
	s_mul_i32 s59, s58, 31
	v_mfma_f32_16x16x32_bf16 v[26:29], v[30:33], v[2:5], v[26:29]
	ds_read_b128 v[30:33], v34 offset:512
	ds_read_b128 v[34:37], v35 offset:512
	s_addk_i32 s59, 0xff27
	s_lshl_b32 s31, s31, 13
	s_waitcnt lgkmcnt(1)
	v_mfma_f32_16x16x32_bf16 v[30:33], v[30:33], v[6:9], 0
	s_and_b32 s58, s31, 0xe000
	v_add_u32_e32 v118, s58, v61
	v_add_u32_e32 v123, v118, v55
	s_waitcnt lgkmcnt(0)
	v_mfma_f32_16x16x32_bf16 v[30:33], v[34:37], v[2:5], v[30:33]
	v_add_u32_e32 v34, s59, v46
	v_lshl_add_u32 v193, v34, 2, s84
	v_cndmask_b32_e64 v35, v194, v193, s[40:41]
	ds_read_b32 v110, v35
	v_add_u32_e32 v122, v118, v41
	ds_read_b128 v[118:121], v123
	v_cndmask_b32_e64 v35, v195, v193, s[42:43]
	ds_read_b32 v111, v35 offset:4
	v_cndmask_b32_e64 v35, v196, v193, s[44:45]
	ds_read_b32 v112, v35 offset:8
	v_cndmask_b32_e64 v35, v197, v193, s[46:47]
	ds_read_b32 v113, v35 offset:12
	v_cndmask_b32_e64 v35, v198, v193, s[48:49]
	ds_read_b32 v114, v35 offset:16
	v_cndmask_b32_e64 v35, v199, v193, s[50:51]
	ds_read_b32 v115, v35 offset:20
	v_cndmask_b32_e64 v35, v200, v193, s[52:53]
	v_cndmask_b32_e64 v34, v201, v193, s[54:55]
	ds_read_b32 v116, v35 offset:24
	ds_read_b32 v117, v34 offset:28
	ds_read_b128 v[34:37], v122
	s_waitcnt lgkmcnt(0)
	v_mfma_f32_16x16x32_bf16 v[34:37], v[34:37], v[6:9], 0
	s_cmp_eq_u32 s80, s64
	v_mfma_f32_16x16x32_bf16 v[34:37], v[118:121], v[2:5], v[34:37]
	ds_read_b128 v[118:121], v122 offset:512
	ds_read_b128 v[122:125], v123 offset:512
	s_waitcnt lgkmcnt(0)
	s_barrier
	s_waitcnt lgkmcnt(1)
	v_mfma_f32_16x16x32_bf16 v[6:9], v[118:121], v[6:9], 0
	s_waitcnt lgkmcnt(0)
	v_mfma_f32_16x16x32_bf16 v[2:5], v[122:125], v[2:5], v[6:9]
	s_cbranch_scc1 .LBB0_453
	s_lshl_b32 s31, s64, 17
	s_add_u32 s58, s21, s31
	s_addc_u32 s59, s83, 0
	s_nop 1
	v_lshl_add_u64 v[6:7], s[58:59], 0, v[50:51]
	v_lshl_add_u64 v[6:7], v[6:7], 0, s[22:23]
	s_lshl_b32 s31, s64, 13
	v_lshl_add_u64 v[6:7], v[6:7], 0, v[0:1]
	s_mov_b64 s[58:59], 0x100000
	s_and_b32 s31, s31, 0xe000
	v_lshl_add_u64 v[6:7], v[6:7], 0, s[58:59]
	s_add_i32 m0, s86, s31
	s_nop 0
	global_load_lds_dwordx4 v[6:7], off

; #define LAS __attribute__((address_space(3)))
; #define MFMA16(a, b, c) __builtin_amdgcn_mfma_f32_16x16x32_bf16((a), (b), (c), 0, 0, 0)
; __device__ __forceinline__ int att_fk(int key) { return ((key >> 3) & 3) + 4 * ((key >> 1) & 1); }
; __device__ __forceinline__ void attn_phase(const bf16_t* Q, const bf16_t* Kb, const bf16_t* VTa, const float* rpb, bf16_t* Y, LAS unsigned char* lds, int bx, int G, int tid, int wave, int lane) {
;     ...
; #pragma unroll
;             for (int ii = 0; ii < 4; ++ii) {
;                 const int i = 4 * hf + ii, dr = rs + i - r + 7;
;                 float bia[8];
; #pragma unroll
;                 for (int j = 0; j < 8; ++j) bia[j] = rl[((unsigned)(j - wlo) < (unsigned)wwd) ? dr * 31 + dci0 + j : 480];
; #pragma unroll
;                 for (int ta = 0; ta < 2; ++ta) {
;                     const int key = cs + 8 * (fr >> 2) + 4 * ta + (fr & 3), fk = att_fk(key);
;                     const LAS unsigned char* kp = KL + ((rs + i) & 7) * 8192 + key * 128;
;                     const bf16x8 kf0 = *(const LAS bf16x8*)(kp + ((fq ^ fk) << 4)), kf1 = *(const LAS bf16x8*)(kp + (((4 + fq) ^ fk) << 4));
;                     f32x4 a = {0.f, 0.f, 0.f, 0.f};
;                     a = MFMA16(kf0, qf0, a); a = MFMA16(kf1, qf1, a);
; #pragma unroll
;                     for (int idx = 0; idx < 4; ++idx) { a[idx] += bia[4 * ta + idx]; mx = fmaxf(mx, a[idx]); }
;                     s[ii][ta] = a;
;                 }
;             }
.LBB0_465:
	s_or_b32 s20, s93, 7
	s_max_i32 s30, s20, 4
	s_add_i32 s30, s30, -4
	s_min_u32 s30, s30, 0x78
	s_add_i32 s31, s30, s85
	s_sub_i32 s60, s31, s20
	s_lshl_b32 s31, s31, 13
	v_mad_u64_u32 v[10:11], s[60:61], s60, 31, v[46:47]
	s_and_b32 s31, s31, 0xe000
	s_waitcnt vmcnt(1)
	v_lshl_add_u32 v190, v10, 2, s84
	v_cndmask_b32_e64 v11, v194, v190, s[40:41]
	v_add_u32_e32 v14, s31, v61
	s_waitcnt lgkmcnt(0)
	s_barrier
	v_add_u32_e32 v27, v14, v55
	ds_read_b32 v18, v11
	v_add_u32_e32 v26, v14, v41
	ds_read_b128 v[14:17], v27
	v_cndmask_b32_e64 v11, v195, v190, s[42:43]
	ds_read_b32 v19, v11 offset:4
	v_cndmask_b32_e64 v11, v196, v190, s[44:45]
	ds_read_b32 v20, v11 offset:8
	v_cndmask_b32_e64 v11, v197, v190, s[46:47]
	ds_read_b32 v21, v11 offset:12
	v_cndmask_b32_e64 v11, v198, v190, s[48:49]
	ds_read_b32 v22, v11 offset:16
	v_cndmask_b32_e64 v11, v199, v190, s[50:51]
	ds_read_b32 v23, v11 offset:20
	v_cndmask_b32_e64 v11, v200, v190, s[52:53]
	v_cndmask_b32_e64 v10, v201, v190, s[54:55]
	ds_read_b32 v24, v11 offset:24
	ds_read_b32 v25, v10 offset:28
	ds_read_b128 v[10:13], v26
	s_waitcnt vmcnt(0) lgkmcnt(0)
	v_mfma_f32_16x16x32_bf16 v[10:13], v[10:13], v[6:9], 0
	s_add_i32 s31, s30, s89
	s_sub_i32 s60, s31, s20
	s_lshl_b32 s31, s31, 13
	v_mfma_f32_16x16x32_bf16 v[14:17], v[14:17], v[2:5], v[10:13]
	s_and_b32 s31, s31, 0xe000
	s_nop 6
	v_add_f32_e32 v13, v18, v14
	v_add_f32_e32 v12, v19, v15
	v_max3_f32 v14, v13, s6, v12
	v_add_f32_e32 v11, v20, v16
	v_add_f32_e32 v10, v21, v17
	v_max3_f32 v28, v14, v11, v10
	ds_read_b128 v[14:17], v26 offset:512
	ds_read_b128 v[18:21], v27 offset:512
	s_waitcnt lgkmcnt(1)
	v_mfma_f32_16x16x32_bf16 v[14:17], v[14:17], v[6:9], 0
	s_waitcnt lgkmcnt(0)
	v_mfma_f32_16x16x32_bf16 v[18:21], v[18:21], v[2:5], v[14:17]
	s_nop 7
	v_add_f32_e32 v17, v22, v18
	v_add_f32_e32 v16, v23, v19
	v_max3_f32 v18, v28, v17, v16
	v_add_f32_e32 v15, v24, v20
	v_add_f32_e32 v14, v25, v21
	v_max3_f32 v26, v18, v15, v14
	v_mad_u64_u32 v[18:19], s[60:61], s60, 31, v[46:47]
	v_lshl_add_u32 v191, v18, 2, s84
	v_cndmask_b32_e64 v19, v194, v191, s[40:41]
	v_add_u32_e32 v22, s31, v61
	v_add_u32_e32 v63, v22, v55
	ds_read_b32 v27, v19
	v_add_u32_e32 v37, v22, v41
	ds_read_b128 v[22:25], v63
	v_cndmask_b32_e64 v19, v195, v191, s[42:43]
	ds_read_b32 v28, v19 offset:4
	v_cndmask_b32_e64 v19, v196, v191, s[44:45]
	ds_read_b32 v29, v19 offset:8
	v_cndmask_b32_e64 v19, v197, v191, s[46:47]
	ds_read_b32 v30, v19 offset:12
	v_cndmask_b32_e64 v19, v198, v191, s[48:49]
	ds_read_b32 v32, v19 offset:16
	v_cndmask_b32_e64 v19, v199, v191, s[50:51]
	ds_read_b32 v33, v19 offset:20
	v_cndmask_b32_e64 v19, v200, v191, s[52:53]
	v_cndmask_b32_e64 v18, v201, v191, s[54:55]
	ds_read_b32 v35, v19 offset:24
	ds_read_b32 v36, v18 offset:28
	ds_read_b128 v[18:21], v37
	s_waitcnt lgkmcnt(0)
	v_mfma_f32_16x16x32_bf16 v[18:21], v[18:21], v[6:9], 0
	s_add_i32 s31, s30, s90
	s_sub_i32 s60, s31, s20
	s_lshl_b32 s31, s31, 13
	v_mfma_f32_16x16x32_bf16 v[22:25], v[22:25], v[2:5], v[18:21]
	s_and_b32 s31, s31, 0xe000
	v_add_u32_e32 v73, s31, v61
	v_add_u32_e32 v75, v73, v41
	v_add_u32_e32 v73, v73, v55
	s_add_i32 s31, s30, s91
	s_nop 2
	v_add_f32_e32 v22, v27, v22
	v_add_f32_e32 v21, v28, v23
	v_max3_f32 v18, v26, v22, v21
	v_add_f32_e32 v20, v29, v24
	v_add_f32_e32 v19, v30, v25
	ds_read_b128 v[24:27], v37 offset:512
	ds_read_b128 v[92:95], v63 offset:512
	s_waitcnt lgkmcnt(1)
	v_mfma_f32_16x16x32_bf16 v[24:27], v[24:27], v[6:9], 0
	v_max3_f32 v18, v18, v20, v19
	s_waitcnt lgkmcnt(0)
	v_mfma_f32_16x16x32_bf16 v[24:27], v[92:95], v[2:5], v[24:27]
	ds_read_b128 v[92:95], v73
	s_nop 6
	v_add_f32_e32 v23, v32, v24
	v_add_f32_e32 v28, v33, v25
	v_mad_u64_u32 v[24:25], s[60:61], s60, 31, v[46:47]
	v_lshl_add_u32 v192, v24, 2, s84
	v_cndmask_b32_e64 v25, v194, v192, s[40:41]
	ds_read_b32 v32, v25
	v_cndmask_b32_e64 v25, v195, v192, s[42:43]
	ds_read_b32 v33, v25 offset:4
	v_cndmask_b32_e64 v25, v196, v192, s[44:45]
	v_add_f32_e32 v29, v35, v26
	ds_read_b32 v35, v25 offset:8
	v_cndmask_b32_e64 v25, v197, v192, s[46:47]
	v_add_f32_e32 v30, v36, v27
	ds_read_b32 v36, v25 offset:12
	v_cndmask_b32_e64 v25, v198, v192, s[48:49]
	ds_read_b32 v37, v25 offset:16
	v_cndmask_b32_e64 v25, v199, v192, s[50:51]
	ds_read_b32 v63, v25 offset:20
	v_cndmask_b32_e64 v25, v200, v192, s[52:53]
	v_cndmask_b32_e64 v24, v201, v192, s[54:55]
	ds_read_b32 v65, v25 offset:24
	ds_read_b32 v71, v24 offset:28
	ds_read_b128 v[24:27], v75
	s_waitcnt lgkmcnt(0)
	v_mfma_f32_16x16x32_bf16 v[24:27], v[24:27], v[6:9], 0
	s_sub_i32 s60, s31, s20
	s_lshl_b32 s31, s31, 13
	s_and_b32 s31, s31, 0xe000
	v_mfma_f32_16x16x32_bf16 v[24:27], v[92:95], v[2:5], v[24:27]
	v_add_u32_e32 v89, s31, v61
	v_add_u32_e32 v91, v89, v41
	v_add_u32_e32 v89, v89, v55
	v_max3_f32 v18, v18, v23, v28
	v_max3_f32 v18, v18, v29, v30
	s_nop 2
	v_add_f32_e32 v32, v32, v24
	v_add_f32_e32 v33, v33, v25
	v_add_f32_e32 v35, v35, v26
	v_add_f32_e32 v36, v36, v27
	ds_read_b128 v[24:27], v75 offset:512
	ds_read_b128 v[92:95], v73 offset:512
	s_waitcnt lgkmcnt(1)
	v_mfma_f32_16x16x32_bf16 v[24:27], v[24:27], v[6:9], 0
	v_max3_f32 v18, v18, v32, v33
	v_max3_f32 v18, v18, v35, v36
	s_waitcnt lgkmcnt(0)
	v_mfma_f32_16x16x32_bf16 v[24:27], v[92:95], v[2:5], v[24:27]
	ds_read_b128 v[92:95], v89
	s_nop 6
	v_add_f32_e32 v37, v37, v24
	v_add_f32_e32 v63, v63, v25
	v_mad_u64_u32 v[24:25], s[60:61], s60, 31, v[46:47]
	v_lshl_add_u32 v193, v24, 2, s84
	v_cndmask_b32_e64 v25, v194, v193, s[40:41]
	ds_read_b32 v73, v25
	v_cndmask_b32_e64 v25, v195, v193, s[42:43]
	ds_read_b32 v75, v25 offset:4
	v_cndmask_b32_e64 v25, v196, v193, s[44:45]
	ds_read_b32 v77, v25 offset:8
	v_cndmask_b32_e64 v25, v197, v193, s[46:47]
	ds_read_b32 v79, v25 offset:12
	v_cndmask_b32_e64 v25, v198, v193, s[48:49]
	ds_read_b32 v81, v25 offset:16
	v_cndmask_b32_e64 v25, v199, v193, s[50:51]
	ds_read_b32 v83, v25 offset:20
	v_cndmask_b32_e64 v25, v200, v193, s[52:53]
	v_cndmask_b32_e64 v24, v201, v193, s[54:55]
	v_add_f32_e32 v65, v65, v26
	v_add_f32_e32 v71, v71, v27
	ds_read_b32 v85, v25 offset:24
	ds_read_b32 v87, v24 offset:28
	ds_read_b128 v[24:27], v91
	s_waitcnt lgkmcnt(0)
	v_mfma_f32_16x16x32_bf16 v[24:27], v[24:27], v[6:9], 0
	v_max3_f32 v18, v18, v37, v63
	v_max3_f32 v18, v18, v65, v71
	v_mfma_f32_16x16x32_bf16 v[24:27], v[92:95], v[2:5], v[24:27]
	s_nop 7
	v_add_f32_e32 v73, v73, v24
	v_add_f32_e32 v75, v75, v25
	v_add_f32_e32 v77, v77, v26
	v_add_f32_e32 v79, v79, v27
	ds_read_b128 v[24:27], v91 offset:512
	ds_read_b128 v[92:95], v89 offset:512
	s_waitcnt lgkmcnt(1)
	v_mfma_f32_16x16x32_bf16 v[6:9], v[24:27], v[6:9], 0
	v_max3_f32 v18, v18, v73, v75
	v_max3_f32 v18, v18, v77, v79
	s_waitcnt lgkmcnt(0)
	s_waitcnt lgkmcnt(0)
	v_mfma_f32_16x16x32_bf16 v[2:5], v[92:95], v[2:5], v[6:9]
	s_barrier
; __device__ __forceinline__ float fast_exp2(float x) { return __builtin_amdgcn_exp2f(x); }
; __device__ __forceinline__ u32x4 pack8(f32x4 a, f32x4 b) { u32x4 w; w.x = cvt_pk_bf16(a[0], a[1]); w.y = cvt_pk_bf16(a[2], a[3]); w.z = cvt_pk_bf16(b[0], b[1]); w.w = cvt_pk_bf16(b[2], b[3]); return w; }
; #define SCHED_FENCE() __builtin_amdgcn_sched_barrier(0)
; #define ATT_BAR() do { asm volatile("s_waitcnt lgkmcnt(0)" ::: "memory"); __builtin_amdgcn_s_barrier(); asm volatile("" ::: "memory"); } while (0)
; __device__ __forceinline__ void attn_phase(const bf16_t* Q, const bf16_t* Kb, const bf16_t* VTa, const float* rpb, bf16_t* Y, LAS unsigned char* lds, int bx, int G, int tid, int wave, int lane) {
;     ...
;             mx = fmaxf(mx, __shfl_xor(mx, 16)); mx = fmaxf(mx, __shfl_xor(mx, 32));
;             float l = 0.f;
;             bf16x8 pb[4];
; #pragma unroll
;             for (int ii = 0; ii < 4; ++ii) {
;                 f32x4 p0, p1;
; #pragma unroll
;                 for (int idx = 0; idx < 4; ++idx) { p0[idx] = fast_exp2((s[ii][0][idx] - mx) * 1.4426950409f); p1[idx] = fast_exp2((s[ii][1][idx] - mx) * 1.4426950409f); }
;                 l += (p0[0] + p0[1]) + (p0[2] + p0[3]) + (p1[0] + p1[1]) + (p1[2] + p1[3]);
;                 const u32x4 pw = pack8(p0, p1); pb[ii] = __builtin_bit_cast(bf16x8, pw);
;             }
;             l += __shfl_xor(l, 16); l += __shfl_xor(l, 32);
;             SCHED_FENCE();
;             if (newrow) asm volatile("s_waitcnt vmcnt(3)" ::: "memory"); else if (has_next) asm volatile("s_waitcnt vmcnt(2)" ::: "memory"); else asm volatile("s_waitcnt vmcnt(0)" ::: "memory");
;             ATT_BAR();
	s_nop 6
	v_add_f32_e32 v24, v81, v2
	v_add_f32_e32 v25, v83, v3
	v_max3_f32 v2, v18, v24, v25
	v_add_f32_e32 v26, v85, v4
	v_add_f32_e32 v27, v87, v5
	v_max3_f32 v2, v2, v26, v27
	ds_bpermute_b32 v3, v31, v2
	s_waitcnt lgkmcnt(0)
	v_max_f32_e32 v3, v3, v3
	v_max_f32_e32 v2, v2, v3
	ds_bpermute_b32 v3, v34, v2
	s_waitcnt lgkmcnt(0)
	v_max_f32_e32 v3, v3, v3
	v_max_f32_e32 v18, v2, v3
	v_sub_f32_e32 v3, v17, v18
	v_sub_f32_e32 v4, v12, v18
	v_sub_f32_e32 v5, v16, v18
	v_mul_f32_e32 v3, 0x3fb8aa3b, v3
	v_mul_f32_e32 v4, 0x3fb8aa3b, v4
	v_mul_f32_e32 v5, 0x3fb8aa3b, v5
	v_sub_f32_e32 v2, v13, v18
	v_exp_f32_e32 v6, v3
	v_exp_f32_e32 v3, v4
	v_exp_f32_e32 v4, v5
	v_sub_f32_e32 v5, v11, v18
	v_sub_f32_e32 v8, v10, v18
	v_mul_f32_e32 v2, 0x3fb8aa3b, v2
	v_mul_f32_e32 v5, 0x3fb8aa3b, v5
	v_mul_f32_e32 v8, 0x3fb8aa3b, v8
	v_exp_f32_e32 v2, v2
	v_exp_f32_e32 v5, v5
	v_sub_f32_e32 v7, v15, v18
	v_exp_f32_e32 v8, v8
	v_sub_f32_e32 v9, v14, v18
	v_mul_f32_e32 v7, 0x3fb8aa3b, v7
	v_mul_f32_e32 v9, 0x3fb8aa3b, v9
	v_exp_f32_e32 v7, v7
	v_exp_f32_e32 v9, v9
	v_add_f32_e32 v10, v2, v3
	v_add_f32_e32 v11, v5, v8
	v_add_f32_e32 v10, v10, v11
	v_add_f32_e32 v11, v6, v4
	v_add_f32_e32 v10, v11, v10
	v_add_f32_e32 v11, v7, v9
	v_cvt_pk_bf16_f32 v2, v2, v3
	v_cvt_pk_bf16_f32 v3, v5, v8
	v_cvt_pk_bf16_f32 v4, v6, v4
	v_cvt_pk_bf16_f32 v5, v7, v9
	v_sub_f32_e32 v7, v23, v18
	v_mul_f32_e32 v7, 0x3fb8aa3b, v7
	v_add_f32_e32 v10, v11, v10
	v_sub_f32_e32 v6, v22, v18
	v_exp_f32_e32 v8, v7
	v_sub_f32_e32 v7, v21, v18
	v_sub_f32_e32 v11, v20, v18
	v_sub_f32_e32 v13, v19, v18
	v_mul_f32_e32 v6, 0x3fb8aa3b, v6
	v_mul_f32_e32 v7, 0x3fb8aa3b, v7
	v_sub_f32_e32 v9, v28, v18
	v_mul_f32_e32 v11, 0x3fb8aa3b, v11
	v_mul_f32_e32 v13, 0x3fb8aa3b, v13
	v_exp_f32_e32 v6, v6
	v_exp_f32_e32 v7, v7
	v_mul_f32_e32 v9, 0x3fb8aa3b, v9
	v_exp_f32_e32 v11, v11
	v_sub_f32_e32 v12, v29, v18
	v_exp_f32_e32 v13, v13
	v_sub_f32_e32 v14, v30, v18
	v_exp_f32_e32 v9, v9
	v_mul_f32_e32 v12, 0x3fb8aa3b, v12
	v_mul_f32_e32 v14, 0x3fb8aa3b, v14
	v_exp_f32_e32 v12, v12
	v_exp_f32_e32 v14, v14
	v_add_f32_e32 v15, v6, v7
	v_add_f32_e32 v16, v11, v13
	v_add_f32_e32 v15, v15, v16
	v_add_f32_e32 v16, v8, v9
	v_add_f32_e32 v15, v16, v15
	v_add_f32_e32 v16, v12, v14
	v_add_f32_e32 v10, 0, v10
	v_add_f32_e32 v15, v16, v15
	v_add_f32_e32 v10, v15, v10
	v_cvt_pk_bf16_f32 v6, v6, v7
	v_cvt_pk_bf16_f32 v7, v11, v13
	v_sub_f32_e32 v11, v32, v18
	v_sub_f32_e32 v13, v33, v18
	v_sub_f32_e32 v15, v35, v18
	v_sub_f32_e32 v17, v36, v18
	v_cvt_pk_bf16_f32 v8, v8, v9
	v_cvt_pk_bf16_f32 v9, v12, v14
	v_mul_f32_e32 v11, 0x3fb8aa3b, v11
	v_sub_f32_e32 v12, v37, v18
	v_mul_f32_e32 v13, 0x3fb8aa3b, v13
	v_sub_f32_e32 v14, v63, v18
	v_mul_f32_e32 v15, 0x3fb8aa3b, v15
	v_mul_f32_e32 v17, 0x3fb8aa3b, v17
	v_exp_f32_e32 v11, v11
	v_mul_f32_e32 v12, 0x3fb8aa3b, v12
	v_exp_f32_e32 v13, v13
	v_mul_f32_e32 v14, 0x3fb8aa3b, v14
	v_exp_f32_e32 v15, v15
	v_sub_f32_e32 v16, v65, v18
	v_exp_f32_e32 v17, v17
	v_sub_f32_e32 v19, v71, v18
	v_exp_f32_e32 v12, v12
	v_exp_f32_e32 v14, v14
	v_mul_f32_e32 v16, 0x3fb8aa3b, v16
	v_mul_f32_e32 v19, 0x3fb8aa3b, v19
	v_exp_f32_e32 v16, v16
	v_exp_f32_e32 v19, v19
	v_add_f32_e32 v20, v11, v13
	v_add_f32_e32 v21, v15, v17
	v_add_f32_e32 v20, v20, v21
	v_add_f32_e32 v21, v12, v14
	v_add_f32_e32 v20, v21, v20
	v_add_f32_e32 v21, v16, v19
	v_add_f32_e32 v20, v21, v20
	v_sub_f32_e32 v21, v24, v18
	v_mul_f32_e32 v21, 0x3fb8aa3b, v21
	v_add_f32_e32 v10, v20, v10
	v_sub_f32_e32 v20, v73, v18
	v_exp_f32_e32 v22, v21
	v_sub_f32_e32 v21, v75, v18
	v_sub_f32_e32 v23, v25, v18
	v_sub_f32_e32 v24, v77, v18
	v_sub_f32_e32 v25, v26, v18
	v_sub_f32_e32 v26, v79, v18
	v_mul_f32_e32 v20, 0x3fb8aa3b, v20
	v_mul_f32_e32 v21, 0x3fb8aa3b, v21
	v_mul_f32_e32 v24, 0x3fb8aa3b, v24
	v_mul_f32_e32 v26, 0x3fb8aa3b, v26
	v_exp_f32_e32 v20, v20
	v_exp_f32_e32 v21, v21
	v_mul_f32_e32 v23, 0x3fb8aa3b, v23
	v_exp_f32_e32 v24, v24
	v_exp_f32_e32 v26, v26
	v_sub_f32_e32 v27, v27, v18
	v_exp_f32_e32 v23, v23
	v_mul_f32_e32 v25, 0x3fb8aa3b, v25
	v_mul_f32_e32 v27, 0x3fb8aa3b, v27
	v_exp_f32_e32 v25, v25
	v_exp_f32_e32 v27, v27
	v_add_f32_e32 v28, v20, v21
	v_add_f32_e32 v29, v24, v26
	v_add_f32_e32 v28, v28, v29
	v_add_f32_e32 v29, v22, v23
	v_add_f32_e32 v28, v29, v28
	v_add_f32_e32 v29, v25, v27
	v_add_f32_e32 v28, v29, v28
	v_add_f32_e32 v28, v28, v10
	ds_bpermute_b32 v29, v31, v28
	v_cvt_pk_bf16_f32 v10, v11, v13
	v_cvt_pk_bf16_f32 v11, v15, v17
	v_cvt_pk_bf16_f32 v12, v12, v14
	v_cvt_pk_bf16_f32 v13, v16, v19
	s_waitcnt lgkmcnt(0)
	v_add_f32_e32 v14, v28, v29
	ds_bpermute_b32 v15, v34, v14
	v_cvt_pk_bf16_f32 v20, v20, v21
	v_cvt_pk_bf16_f32 v21, v24, v26
	v_cvt_pk_bf16_f32 v22, v22, v23
	v_cvt_pk_bf16_f32 v23, v25, v27
	s_waitcnt lgkmcnt(0)
	v_add_f32_e32 v19, v14, v15
	s_or_b32 s30, s30, s87
	s_lshl_b32 s30, s30, 13
	s_waitcnt vmcnt(0)
	s_and_b32 s31, s30, 0xe000
	s_waitcnt lgkmcnt(0)
	s_barrier
; #define LAS __attribute__((address_space(3)))
; __device__ __forceinline__ unsigned cvt_pk_bf16(float lo, float hi) { unsigned r; asm volatile("v_cvt_pk_bf16_f32 %0, %1, %2" : "=v"(r) : "v"(lo), "v"(hi)); return r; }
; #define MFMA16(a, b, c) __builtin_amdgcn_mfma_f32_16x16x32_bf16((a), (b), (c), 0, 0, 0)
; __device__ __forceinline__ int att_fv(int dh) { return (dh >> 1) & 7; }
; __device__ __forceinline__ void attn_phase(const bf16_t* Q, const bf16_t* Kb, const bf16_t* VTa, const float* rpb, bf16_t* Y, LAS unsigned char* lds, int bx, int G, int tid, int wave, int lane) {
;     ...
;             f32x4 o[4];
; #pragma unroll
;             for (int dt = 0; dt < 4; ++dt) o[dt] = (f32x4){0.f, 0.f, 0.f, 0.f};
; #pragma unroll
;             for (int ii = 0; ii < 4; ++ii) {
;                 const int i = 4 * hf + ii;
; #pragma unroll
;                 for (int dt = 0; dt < 4; ++dt) { const int dh = 16 * dt + fr;
;                     const bf16x8 vf = *(const LAS bf16x8*)(VL + ((rs + i) & 7) * 8192 + dh * 128 + ((((cs >> 3) + fq) ^ att_fv(dh)) << 4));
;                     o[dt] = MFMA16(vf, pb[ii], o[dt]); }
;             }
;             LAS float* ml = (LAS float*)(lds + 131072 + 2048) + (size_t)(g * 64 + lane) * 2;
;             LAS u32x2* ol = (LAS u32x2*)(lds + 131072 + 4096) + (size_t)(g * 64 + lane) * 4;
;             if (hf == 1) {
; #pragma unroll
;                 for (int dt = 0; dt < 4; ++dt) { u32x2 w; w.x = cvt_pk_bf16(o[dt][0], o[dt][1]); w.y = cvt_pk_bf16(o[dt][2], o[dt][3]); ol[dt] = w; }
;                 ml[0] = mx; ml[1] = l;
;             }
	v_add_u32_e32 v32, s31, v49
	s_add_i32 s31, s30, 0x2000
	s_and_b32 s31, s31, 0xe000
	v_add_u32_e32 v33, s31, v49
	s_add_i32 s31, s30, 0x4000
	s_and_b32 s31, s31, 0xe000
	v_add_u32_e32 v34, s31, v49
	s_addk_i32 s30, 0x6000
	s_and_b32 s30, s30, 0xe000
	v_add_u32_e32 v35, s30, v49
	s_and_b64 vcc, exec, s[58:59]
	ds_read_b128 v[108:111], v32
	ds_read_b128 v[112:115], v32 offset:2048
	ds_read_b128 v[116:119], v32 offset:4096
	ds_read_b128 v[120:123], v32 offset:6144
	ds_read_b128 v[124:127], v33
	ds_read_b128 v[128:131], v33 offset:2048
	ds_read_b128 v[132:135], v33 offset:4096
	ds_read_b128 v[136:139], v33 offset:6144
	ds_read_b128 v[140:143], v34
	ds_read_b128 v[144:147], v34 offset:2048
	ds_read_b128 v[148:151], v34 offset:4096
	ds_read_b128 v[152:155], v34 offset:6144
	ds_read_b128 v[174:177], v35
	ds_read_b128 v[178:181], v35 offset:2048
	ds_read_b128 v[182:185], v35 offset:4096
	ds_read_b128 v[186:189], v35 offset:6144
	s_waitcnt lgkmcnt(12)
	v_mfma_f32_16x16x32_bf16 v[14:17], v[108:111], v[2:5], 0
	v_mfma_f32_16x16x32_bf16 v[24:27], v[112:115], v[2:5], 0
	v_mfma_f32_16x16x32_bf16 v[28:31], v[116:119], v[2:5], 0
	v_mfma_f32_16x16x32_bf16 v[2:5], v[120:123], v[2:5], 0
	s_waitcnt lgkmcnt(8)
	v_mfma_f32_16x16x32_bf16 v[14:17], v[124:127], v[6:9], v[14:17]
	v_mfma_f32_16x16x32_bf16 v[24:27], v[128:131], v[6:9], v[24:27]
	v_mfma_f32_16x16x32_bf16 v[28:31], v[132:135], v[6:9], v[28:31]
	v_mfma_f32_16x16x32_bf16 v[2:5], v[136:139], v[6:9], v[2:5]
	s_waitcnt lgkmcnt(4)
	v_mfma_f32_16x16x32_bf16 v[14:17], v[140:143], v[10:13], v[14:17]
	v_mfma_f32_16x16x32_bf16 v[24:27], v[144:147], v[10:13], v[24:27]
	v_mfma_f32_16x16x32_bf16 v[28:31], v[148:151], v[10:13], v[28:31]
	v_mfma_f32_16x16x32_bf16 v[2:5], v[152:155], v[10:13], v[2:5]
	s_waitcnt lgkmcnt(0)
	v_mfma_f32_16x16x32_bf16 v[14:17], v[174:177], v[20:23], v[14:17]
	v_mfma_f32_16x16x32_bf16 v[10:13], v[178:181], v[20:23], v[24:27]
	v_mfma_f32_16x16x32_bf16 v[6:9], v[182:185], v[20:23], v[28:31]
	v_mfma_f32_16x16x32_bf16 v[2:5], v[186:189], v[20:23], v[2:5]
	s_nop 7
	v_add_u32_e32 v20, 0, v59
	v_add_u32_e32 v21, 0, v57
	v_add_u32_e32 v20, 0x21000, v20
	v_add_u32_e32 v21, 0x20800, v21
	s_cbranch_vccnz .LBB0_467
	v_cvt_pk_bf16_f32 v22, v14, v15
	v_cvt_pk_bf16_f32 v23, v16, v17
	ds_write_b64 v20, v[22:23]
	v_cvt_pk_bf16_f32 v22, v10, v11
	v_cvt_pk_bf16_f32 v23, v12, v13
	ds_write_b64 v20, v[22:23] offset:8
	v_cvt_pk_bf16_f32 v22, v6, v7
	v_cvt_pk_bf16_f32 v23, v8, v9
	ds_write_b64 v20, v[22:23] offset:16
	v_cvt_pk_bf16_f32 v22, v2, v3
	v_cvt_pk_bf16_f32 v23, v4, v5
	ds_write_b64 v20, v[22:23] offset:24
	ds_write_b64 v21, v[18:19]
